# strategy 4: one static s_setprio 1 for waves 0-3 (leading half) during the three GEMM phases, back to 0 at phase end
# baseline (speedup 1.0000x reference)
.LBB0_177:
	v_mov_b32_e32 v6, v0
	v_readlane_b32 s6, v255, 6
	v_readlane_b32 s7, v255, 7
	v_ashrrev_i32_e32 v16, 6, v6
	s_andn2_b64 vcc, exec, s[6:7]
	v_readfirstlane_b32 s14, v16
	s_cbranch_vccnz .LBB0_197
	v_readfirstlane_b32 s32, v0
	s_nop 3
	s_lshr_b32 s32, s32, 8
	s_cmp_eq_u32 s32, 0
	s_cbranch_scc0 .Lprio_skip_g
	s_setprio 1
.Lprio_skip_g:
	v_lshlrev_b32_e32 v3, 4, v6
	v_add_u32_e32 v2, 0x2000, v3
	v_ashrrev_i32_e32 v4, 31, v2
	v_lshrrev_b32_e32 v4, 22, v4
	v_add_u32_e32 v4, v2, v4
	v_ashrrev_i32_e32 v17, 10, v4
	v_mul_i32_i24_e32 v4, 0x400, v17
	v_sub_u32_e32 v2, v2, v4
	v_lshrrev_b32_e32 v4, 4, v2
	s_ashr_i32 s16, s14, 2
	s_lshl_b32 s35, s14, 10
	v_bitop3_b32 v2, v4, v2, 32 bitop3:0x6c
	s_mul_i32 s6, s95, 0xa300000
	s_cmp_eq_u32 s80, 0
	v_ashrrev_i32_e32 v4, 31, v2
	s_cselect_b32 s7, 0, 0x4200000
	s_waitcnt lgkmcnt(0)
	s_add_u32 s6, s4, s6
	v_lshrrev_b32_e32 v4, 26, v4
	s_addc_u32 s10, s5, 0
	v_add_u32_e32 v4, v2, v4
	v_lshlrev_b32_e32 v7, 3, v17
	s_add_u32 s6, s6, s7
	v_ashrrev_i32_e32 v18, 6, v4
	v_and_b32_e32 v7, -16, v7
	s_addc_u32 s7, s10, 0
	v_add_u32_e32 v7, v18, v7
	s_add_u32 s36, s6, 0x800000
	v_and_b32_e32 v8, 3, v18
	s_mov_b32 s6, 0xfffe0
	v_lshrrev_b32_e32 v9, 2, v7
	v_lshlrev_b32_e32 v10, 1, v7
	v_and_b32_e32 v4, 0xc0, v4
	v_and_or_b32 v8, v7, s6, v8
	v_and_b32_e32 v9, 4, v9
	v_and_b32_e32 v10, 24, v10
	v_sub_u32_e32 v2, v2, v4
	v_mov_b32_e32 v12, 1
	v_or3_b32 v8, v8, v9, v10
	v_lshlrev_b32_e32 v9, 5, v17
	v_ashrrev_i16_sdwa v2, v12, sext(v2) dst_sel:DWORD dst_unused:UNUSED_PAD src0_sel:DWORD src1_sel:BYTE_0
	v_and_b32_e32 v9, 32, v9
	v_bfe_i32 v19, v2, 0, 16
	v_add_lshl_u32 v4, v9, v19, 1
	v_lshl_add_u32 v2, v8, 12, v4
	v_lshl_add_u32 v166, v7, 12, v4
	v_bfe_i32 v4, v6, 27, 1
	v_lshrrev_b32_e32 v4, 22, v4
	v_add_u32_e32 v4, v3, v4
	v_and_b32_e32 v4, 0xfffffc00, v4
	v_sub_u32_e32 v3, v3, v4
	v_lshrrev_b32_e32 v4, 4, v3
	v_ashrrev_i32_e32 v7, 31, v6
	v_bitop3_b32 v3, v4, v3, 32 bitop3:0x6c
	v_lshrrev_b32_e32 v8, 26, v7
	v_ashrrev_i32_e32 v4, 31, v3
	v_add_u32_e32 v8, v6, v8
	v_lshrrev_b32_e32 v4, 26, v4
	v_ashrrev_i32_e32 v21, 6, v8
	v_add_u32_e32 v4, v3, v4
	v_lshlrev_b32_e32 v8, 3, v21
	v_ashrrev_i32_e32 v20, 6, v4
	v_and_b32_e32 v8, -16, v8
	v_add_u32_e32 v8, v20, v8
	v_and_b32_e32 v9, 3, v20
	v_lshrrev_b32_e32 v10, 2, v8
	v_lshlrev_b32_e32 v11, 1, v8
	v_and_b32_e32 v4, 0xc0, v4
	v_and_or_b32 v9, v8, s6, v9
	v_and_b32_e32 v10, 4, v10
	v_and_b32_e32 v11, 24, v11
	v_sub_u32_e32 v3, v3, v4
	s_addc_u32 s37, s7, 0
	v_or3_b32 v9, v9, v10, v11
	v_lshlrev_b32_e32 v10, 5, v21
	v_ashrrev_i16_sdwa v3, v12, sext(v3) dst_sel:DWORD dst_unused:UNUSED_PAD src0_sel:DWORD src1_sel:BYTE_0
	v_readlane_b32 s6, v255, 13
	v_and_b32_e32 v10, 32, v10
	v_bfe_i32 v22, v3, 0, 16
	v_readlane_b32 s7, v255, 14
	s_add_u32 s6, s36, s6
	v_add_lshl_u32 v3, v10, v22, 1
	s_addc_u32 s7, s37, s7
	s_add_i32 s33, s35, 0
	v_lshl_add_u32 v4, v9, 12, v3
	s_add_i32 m0, s33, 0x10000
	v_lshl_add_u32 v168, v8, 12, v3
	global_load_lds_dwordx4 v4, s[6:7]
	s_add_i32 m0, s33, 0x12000
	s_add_u32 s10, s6, 0x80000
	global_load_lds_dwordx4 v2, s[6:7]
	s_addc_u32 s11, s7, 0
	s_add_i32 m0, s33, 0x14000
	v_mov_b32_e32 v3, v5
	global_load_lds_dwordx4 v4, s[10:11]
	s_add_i32 m0, s33, 0x16000
	v_mov_b32_e32 v169, v5
	global_load_lds_dwordx4 v2, s[10:11]
	v_readlane_b32 s10, v255, 36
	v_readlane_b32 s11, v255, 37
	s_add_u32 s26, s8, s10
	s_addc_u32 s27, s9, s11
	s_add_i32 s38, s33, 0x2000
	s_mov_b32 m0, s33
	s_add_u32 s10, s26, 0x80000
	global_load_lds_dwordx4 v168, s[26:27]
	s_mov_b32 m0, s38
	s_addc_u32 s11, s27, 0
	s_add_i32 s39, s33, 0x4000
	global_load_lds_dwordx4 v166, s[26:27]
	s_mov_b32 m0, s39
	s_add_i32 s40, s33, 0x6000
	global_load_lds_dwordx4 v168, s[10:11]
	s_mov_b32 m0, s40
	v_mov_b32_e32 v167, v5
	global_load_lds_dwordx4 v166, s[10:11]
	s_cmp_eq_u32 s16, 1
	v_mov_b32_e32 v252, 1
	v_lshl_add_u64 v[14:15], s[6:7], 0, v[4:5]
	v_lshl_add_u64 v[12:13], s[6:7], 0, v[2:3]
	v_lshl_add_u64 v[8:9], s[26:27], 0, v[168:169]
	s_cselect_b64 s[10:11], -1, 0
	s_cmp_lg_u32 s16, 1
	v_lshl_add_u64 v[10:11], s[26:27], 0, v[166:167]
	s_cbranch_scc1 .LBB0_180
	s_barrier

.LBB0_197:
	s_setprio 0
	s_waitcnt lgkmcnt(0)
	s_mov_b64 s[4:5], 0
.LBB0_198:
	s_and_b64 vcc, exec, s[4:5]
	s_cbranch_vccz .LBB0_431
	s_and_b32 s42, s95, 0xffff
	s_lshl_b32 s4, s42, 9
	v_writelane_b32 v255, s4, 52
	s_mov_b64 s[4:5], s[70:71]
	v_mov_b32_e32 v2, v0
	v_mov_b32_e32 v6, v0
	v_readlane_b32 s6, v255, 8
	v_readlane_b32 s7, v255, 9
	v_ashrrev_i32_e32 v16, 6, v6
	s_mul_hi_u32 s43, s42, 0xa300000
	s_mul_i32 s44, s42, 0xa300000
	s_lshl_b32 s36, s69, 15
	s_mov_b32 s37, s77
	v_readfirstlane_b32 s22, v16
	s_and_b64 vcc, exec, s[6:7]
	s_cbranch_vccz .LBB0_223
	v_readfirstlane_b32 s32, v0
	s_nop 3
	s_lshr_b32 s32, s32, 8
	s_cmp_eq_u32 s32, 0
	s_cbranch_scc0 .Lprio_skip_z
	s_setprio 1
.Lprio_skip_z:
	v_lshlrev_b32_e32 v3, 4, v6
	v_add_u32_e32 v2, 0x2000, v3
	v_ashrrev_i32_e32 v4, 31, v2
	v_lshrrev_b32_e32 v4, 22, v4
	v_add_u32_e32 v4, v2, v4
	v_ashrrev_i32_e32 v17, 10, v4
	v_mul_i32_i24_e32 v4, 0x400, v17
	v_sub_u32_e32 v2, v2, v4
	s_load_dwordx4 s[12:15], s[4:5], 0x80
	s_load_dwordx4 s[16:19], s[4:5], 0x50
	v_lshrrev_b32_e32 v4, 4, v2
	v_bitop3_b32 v2, v4, v2, 32 bitop3:0x6c
	v_ashrrev_i32_e32 v4, 31, v2
	v_lshrrev_b32_e32 v4, 26, v4
	v_add_u32_e32 v4, v2, v4
	v_lshlrev_b32_e32 v7, 3, v17
	s_waitcnt lgkmcnt(0)
	s_add_u32 s4, s14, s44
	v_ashrrev_i32_e32 v18, 6, v4
	v_and_b32_e32 v7, -16, v7
	s_addc_u32 s5, s15, s43
	v_add_u32_e32 v7, v18, v7
	s_add_u32 s40, s4, 0x8c00000
	v_and_b32_e32 v8, 3, v18
	s_mov_b32 s4, 0xfffe0
	v_lshrrev_b32_e32 v9, 2, v7
	v_lshlrev_b32_e32 v10, 1, v7
	v_and_b32_e32 v4, 0xc0, v4
	v_and_or_b32 v8, v7, s4, v8
	v_and_b32_e32 v9, 4, v9
	v_and_b32_e32 v10, 24, v10
	v_sub_u32_e32 v2, v2, v4
	v_mov_b32_e32 v12, 1
	v_or3_b32 v8, v8, v9, v10
	v_lshlrev_b32_e32 v9, 5, v17
	v_ashrrev_i16_sdwa v2, v12, sext(v2) dst_sel:DWORD dst_unused:UNUSED_PAD src0_sel:DWORD src1_sel:BYTE_0
	v_and_b32_e32 v9, 32, v9
	v_bfe_i32 v19, v2, 0, 16
	v_add_lshl_u32 v4, v9, v19, 1
	v_lshl_add_u32 v2, v8, 12, v4
	v_lshl_add_u32 v166, v7, 12, v4
	v_bfe_i32 v4, v6, 27, 1
	v_lshrrev_b32_e32 v4, 22, v4
	v_add_u32_e32 v4, v3, v4
	v_and_b32_e32 v4, 0xfffffc00, v4
	v_sub_u32_e32 v3, v3, v4
	v_lshrrev_b32_e32 v4, 4, v3
	v_ashrrev_i32_e32 v7, 31, v6
	v_bitop3_b32 v3, v4, v3, 32 bitop3:0x6c
	v_lshrrev_b32_e32 v8, 26, v7
	v_ashrrev_i32_e32 v4, 31, v3
	v_add_u32_e32 v8, v6, v8
	v_lshrrev_b32_e32 v4, 26, v4
	v_ashrrev_i32_e32 v21, 6, v8
	v_add_u32_e32 v4, v3, v4
	v_lshlrev_b32_e32 v8, 3, v21
	v_ashrrev_i32_e32 v20, 6, v4
	v_and_b32_e32 v8, -16, v8
	v_add_u32_e32 v8, v20, v8
	v_and_b32_e32 v9, 3, v20
	v_lshrrev_b32_e32 v10, 2, v8
	v_lshlrev_b32_e32 v11, 1, v8
	v_and_b32_e32 v4, 0xc0, v4
	v_and_or_b32 v9, v8, s4, v9
	v_and_b32_e32 v10, 4, v10
	v_and_b32_e32 v11, 24, v11
	v_sub_u32_e32 v3, v3, v4
	s_addc_u32 s41, s5, 0
	s_ashr_i32 s23, s22, 2
	s_lshl_b32 s45, s22, 10
	v_or3_b32 v9, v9, v10, v11
	v_lshlrev_b32_e32 v10, 5, v21
	v_ashrrev_i16_sdwa v3, v12, sext(v3) dst_sel:DWORD dst_unused:UNUSED_PAD src0_sel:DWORD src1_sel:BYTE_0
	v_readlane_b32 s4, v255, 17
	v_and_b32_e32 v10, 32, v10
	v_bfe_i32 v22, v3, 0, 16
	v_readlane_b32 s5, v255, 18
	s_add_u32 s6, s40, s4
	v_add_lshl_u32 v3, v10, v22, 1
	s_addc_u32 s7, s41, s5
	s_add_i32 s33, s45, 0
	v_lshl_add_u32 v4, v9, 12, v3
	s_add_i32 m0, s33, 0x10000
	v_lshl_add_u32 v168, v8, 12, v3
	global_load_lds_dwordx4 v4, s[6:7]
	s_add_i32 m0, s33, 0x12000
	s_add_u32 s4, s6, 0x80000
	global_load_lds_dwordx4 v2, s[6:7]
	s_addc_u32 s5, s7, 0
	s_add_i32 m0, s33, 0x14000
	s_load_dword s49, s[86:87], 0x0
	global_load_lds_dwordx4 v4, s[4:5]
	s_add_i32 m0, s33, 0x16000
	v_mov_b32_e32 v3, v5
	global_load_lds_dwordx4 v2, s[4:5]
	v_readlane_b32 s4, v255, 32
	v_readlane_b32 s5, v255, 33
	s_add_u32 s8, s12, s4
	s_addc_u32 s9, s13, s5
	s_add_i32 s46, s33, 0x2000
	s_mov_b32 m0, s33
	s_add_u32 s4, s8, 0x80000
	global_load_lds_dwordx4 v168, s[8:9]
	s_mov_b32 m0, s46
	s_addc_u32 s5, s9, 0
	s_add_i32 s47, s33, 0x4000
	global_load_lds_dwordx4 v166, s[8:9]
	s_mov_b32 m0, s47
	s_add_i32 s48, s33, 0x6000
	global_load_lds_dwordx4 v168, s[4:5]
	s_mov_b32 m0, s48
	v_mov_b32_e32 v169, v5
	global_load_lds_dwordx4 v166, s[4:5]
	v_mov_b32_e32 v167, v5
	s_cmp_eq_u32 s23, 1
	v_mov_b32_e32 v252, 1
	v_lshl_add_u64 v[14:15], s[6:7], 0, v[4:5]
	v_lshl_add_u64 v[12:13], s[6:7], 0, v[2:3]
	v_lshl_add_u64 v[8:9], s[8:9], 0, v[168:169]
	s_cselect_b64 s[10:11], -1, 0
	s_cmp_lg_u32 s23, 1
	v_lshl_add_u64 v[10:11], s[8:9], 0, v[166:167]
	s_cbranch_scc1 .LBB0_202
	s_barrier

.LBB0_223:
	s_setprio 0
	v_readlane_b32 s40, v255, 0
	v_readlane_b32 s41, v255, 1
	v_readlane_b32 s33, v255, 2
	s_waitcnt vmcnt(0)
	s_waitcnt vmcnt(0)
	s_barrier
	s_mov_b64 s[4:5], exec
	v_readlane_b32 s6, v255, 3
	v_readlane_b32 s7, v255, 4
	s_and_b64 s[6:7], s[4:5], s[6:7]
	s_xor_b64 s[38:39], s[6:7], s[4:5]
	v_readlane_b32 s46, v255, 29
	s_mov_b32 s47, 0x9c000
	s_mov_b64 exec, s[6:7]
	s_cbranch_execz .LBB0_268
	v_readlane_b32 s4, v255, 27
	s_waitcnt vmcnt(0) expcnt(0) lgkmcnt(0)
	s_nop 0
	v_mov_b32_e32 v2, s4
	ds_read_b32 v4, v2
	v_readlane_b32 s4, v255, 28
	s_waitcnt lgkmcnt(0)
	v_cmp_ne_u32_e32 vcc, 0, v4
	v_mov_b32_e32 v2, s4
	ds_read_b32 v2, v2
	s_cbranch_vccnz .LBB0_238
	s_load_dwordx2 s[8:9], s[86:87], 0x0
	s_load_dword s7, s[86:87], 0x8
	s_add_u32 s4, s40, 0x1000
	s_addc_u32 s5, s41, 0
	s_add_u32 s6, s40, 0x1100
	s_waitcnt lgkmcnt(0)
	s_mul_i32 s30, s9, s8
	s_mul_i32 s30, s30, s7
	s_addc_u32 s7, s41, 0
	s_add_u32 s8, s40, 0x1200
	s_addc_u32 s9, s41, 0
	s_add_u32 s10, s40, 0x1300
	s_addc_u32 s11, s41, 0
	s_mov_b32 s31, 1
	s_mov_b64 s[12:13], 0
	s_branch .LBB0_228

.LBB0_480:
	v_mov_b32_e32 v4, v0
	s_add_i32 s69, s69, 1
	s_andn2_b64 vcc, exec, s[84:85]
	v_readfirstlane_b32 s6, v4
	s_cbranch_vccnz .LBB0_579
	v_readfirstlane_b32 s32, v0
	s_nop 3
	s_lshr_b32 s32, s32, 8
	s_cmp_eq_u32 s32, 0
	s_cbranch_scc0 .Lprio_skip_r
	s_setprio 1
.Lprio_skip_r:
	v_lshlrev_b32_e32 v18, 4, v4
	v_add_u32_e32 v2, 0x2000, v18
	v_ashrrev_i32_e32 v3, 31, v2
	s_mul_i32 s7, s95, 0xa300000
	v_lshrrev_b32_e32 v3, 22, v3
	s_waitcnt lgkmcnt(0)
	s_add_u32 s7, s4, s7
	v_readlane_b32 s24, v255, 50
	v_add_u32_e32 v3, v2, v3
	s_addc_u32 s10, s5, 0
	v_readlane_b32 s25, v255, 51
	v_ashrrev_i32_e32 v3, 10, v3
	s_and_b64 s[8:9], exec, s[24:25]
	v_mul_i32_i24_e32 v6, 0x400, v3
	s_mov_b32 s8, 0x31400000
	v_sub_u32_e32 v2, v2, v6
	s_cselect_b32 s8, 0x47400000, s8
	v_lshrrev_b32_e32 v6, 4, v2
	s_add_u32 s35, s4, s8
	v_bitop3_b32 v2, v6, v2, 32 bitop3:0x6c
	s_addc_u32 s36, s5, 0
	v_ashrrev_i32_e32 v6, 31, v2
	s_cmp_eq_u32 s80, 0
	s_mov_b32 s8, 0x2c00000
	v_lshrrev_b32_e32 v6, 26, v6
	s_cselect_b32 s11, s8, 0x6e00000
	s_and_b64 s[8:9], exec, s[24:25]
	v_add_u32_e32 v6, v2, v6
	v_lshlrev_b32_e32 v8, 3, v3
	s_movk_i32 s8, 0x800
	s_cselect_b32 s9, 0x9b00000, s11
	v_ashrrev_i32_e32 v7, 6, v6
	v_and_b32_e32 v8, -16, v8
	v_lshlrev_b32_e32 v3, 5, v3
	s_cselect_b32 s8, s8, 0x1600
	s_add_u32 s7, s7, s9
	v_add_u32_e32 v8, v7, v8
	v_and_b32_e32 v19, 32, v3
	v_and_b32_e32 v3, 0xc0, v6
	s_addc_u32 s9, s10, 0
	v_and_b32_e32 v7, 3, v7
	s_mov_b32 s10, 0x7fffe0
	v_lshrrev_b32_e32 v9, 2, v8
	v_lshlrev_b32_e32 v10, 1, v8
	v_sub_u32_e32 v2, v2, v3
	v_mov_b32_e32 v12, 1
	v_and_or_b32 v7, v8, s10, v7
	v_and_b32_e32 v9, 4, v9
	v_and_b32_e32 v10, 24, v10
	v_ashrrev_i16_sdwa v2, v12, sext(v2) dst_sel:DWORD dst_unused:UNUSED_PAD src0_sel:DWORD src1_sel:BYTE_0
	v_or3_b32 v7, v7, v9, v10
	v_bfe_i32 v20, v2, 0, 16
	v_mul_u32_u24_e32 v7, s8, v7
	v_add_u32_e32 v3, v19, v20
	v_mul_lo_u32 v21, v8, s8
	v_add_lshl_u32 v2, v7, v3, 1
	v_add_lshl_u32 v212, v3, v21, 1
	v_bfe_i32 v3, v4, 27, 1
	v_lshrrev_b32_e32 v3, 22, v3
	v_add_u32_e32 v3, v18, v3
	v_and_b32_e32 v3, 0xfffffc00, v3
	v_sub_u32_e32 v3, v18, v3
	v_lshrrev_b32_e32 v6, 4, v3
	v_ashrrev_i32_e32 v8, 31, v4
	v_bitop3_b32 v3, v6, v3, 32 bitop3:0x6c
	v_lshrrev_b32_e32 v8, 26, v8
	v_ashrrev_i32_e32 v6, 31, v3
	v_add_u32_e32 v8, v4, v8
	v_lshrrev_b32_e32 v6, 26, v6
	v_ashrrev_i32_e32 v8, 6, v8
	v_add_u32_e32 v6, v3, v6
	v_lshlrev_b32_e32 v9, 3, v8
	v_ashrrev_i32_e32 v7, 6, v6
	v_and_b32_e32 v9, -16, v9
	v_add_u32_e32 v9, v7, v9
	v_and_b32_e32 v7, 3, v7
	s_add_u32 s37, s7, 0x800000
	v_and_or_b32 v7, v9, s10, v7
	v_and_b32_e32 v6, 0xc0, v6
	v_readlane_b32 s10, v255, 21
	s_addc_u32 s38, s9, 0
	s_ashr_i32 s7, s6, 6
	s_lshl_b32 s39, s8, 9
	v_lshrrev_b32_e32 v10, 2, v9
	v_lshlrev_b32_e32 v11, 1, v9
	v_sub_u32_e32 v3, v3, v6
	v_readlane_b32 s11, v255, 22
	s_mov_b32 s14, s10
	s_ashr_i32 s9, s6, 8
	s_lshl_b32 s76, s8, 8
	s_lshl_b32 s40, s7, 10
	v_and_b32_e32 v10, 4, v10
	v_and_b32_e32 v11, 24, v11
	v_lshlrev_b32_e32 v8, 5, v8
	v_ashrrev_i16_sdwa v3, v12, sext(v3) dst_sel:DWORD dst_unused:UNUSED_PAD src0_sel:DWORD src1_sel:BYTE_0
	s_mul_i32 s11, s39, s14
	v_or3_b32 v7, v7, v10, v11
	v_and_b32_e32 v22, 32, v8
	v_bfe_i32 v23, v3, 0, 16
	s_mul_hi_i32 s10, s39, s10
	s_add_u32 s30, s37, s11
	v_mul_u32_u24_e32 v7, s8, v7
	v_add_u32_e32 v3, v22, v23
	s_addc_u32 s31, s38, s10
	s_add_i32 s41, s40, 0
	v_add_lshl_u32 v214, v7, v3, 1
	s_add_i32 m0, s41, 0x10000
	s_mul_i32 s13, s39, s91
	global_load_lds_dwordx4 v214, s[30:31]
	s_add_i32 m0, s41, 0x12000
	s_add_u32 s10, s30, s76
	global_load_lds_dwordx4 v2, s[30:31]
	s_addc_u32 s11, s31, 0
	s_add_i32 m0, s41, 0x14000
	v_mul_lo_u32 v24, v9, s8
	global_load_lds_dwordx4 v214, s[10:11]
	s_add_i32 m0, s41, 0x16000
	s_mul_hi_i32 s12, s39, s91
	s_add_u32 s28, s35, s13
	v_add_lshl_u32 v216, v3, v24, 1
	v_mov_b32_e32 v215, v5
	v_mov_b32_e32 v3, v5
	s_addc_u32 s29, s36, s12
	s_add_i32 s42, s41, 0x2000
	v_lshl_add_u64 v[10:11], s[10:11], 0, v[214:215]
	v_lshl_add_u64 v[12:13], s[10:11], 0, v[2:3]
	global_load_lds_dwordx4 v2, s[10:11]
	s_mov_b32 m0, s41
	s_add_u32 s10, s28, s76
	global_load_lds_dwordx4 v216, s[28:29]
	s_mov_b32 m0, s42
	s_addc_u32 s11, s29, 0
	s_add_i32 s43, s41, 0x4000
	global_load_lds_dwordx4 v212, s[28:29]
	s_mov_b32 m0, s43
	s_add_i32 s44, s41, 0x6000
	global_load_lds_dwordx4 v216, s[10:11]
	s_mov_b32 m0, s44
	v_mov_b32_e32 v217, v5
	global_load_lds_dwordx4 v212, s[10:11]
	v_mov_b32_e32 v213, v5
	s_cmp_eq_u32 s9, 1
	v_mov_b32_e32 v252, 1
	v_lshl_add_u64 v[6:7], s[30:31], 0, v[214:215]
	v_lshl_add_u64 v[8:9], s[30:31], 0, v[2:3]
	v_lshl_add_u64 v[14:15], s[28:29], 0, v[216:217]
	v_lshl_add_u64 v[16:17], s[28:29], 0, v[212:213]
	s_cselect_b64 s[22:23], -1, 0
	s_cmp_lg_u32 s9, 1
	s_cbranch_scc1 .LBB0_483
	s_barrier

.LBB0_579:
	s_setprio 0
	v_readlane_b32 s38, v255, 0
	v_readlane_b32 s39, v255, 1
	v_readlane_b32 s33, v255, 2
	s_waitcnt vmcnt(0)
	s_waitcnt vmcnt(0) lgkmcnt(0)
	s_barrier
	s_mov_b64 s[36:37], exec
	v_readlane_b32 s4, v255, 3
	v_readlane_b32 s5, v255, 4
	s_and_b64 s[4:5], s[36:37], s[4:5]
	s_mov_b64 exec, s[4:5]
	s_cbranch_execz .LBB0_116
	v_readlane_b32 s4, v255, 27
	s_waitcnt vmcnt(0) expcnt(0) lgkmcnt(0)
	s_nop 0
	v_mov_b32_e32 v2, s4
	ds_read_b32 v4, v2
	v_readlane_b32 s4, v255, 28
	s_waitcnt lgkmcnt(0)
	v_cmp_ne_u32_e32 vcc, 0, v4
	v_mov_b32_e32 v2, s4
	ds_read_b32 v2, v2
	s_cbranch_vccnz .LBB0_594
	s_load_dwordx2 s[8:9], s[86:87], 0x4
	s_add_u32 s4, s38, 0x1000
	s_addc_u32 s5, s39, 0
	s_add_u32 s6, s38, 0x1100
	s_addc_u32 s7, s39, 0
	s_waitcnt lgkmcnt(0)
	s_mul_i32 s30, s8, s34
	s_add_u32 s8, s38, 0x1200
	s_mul_i32 s30, s30, s9
	s_addc_u32 s9, s39, 0
	s_add_u32 s10, s38, 0x1300
	s_addc_u32 s11, s39, 0
	s_mov_b32 s31, 1
	s_mov_b64 s[12:13], 0
	s_branch .LBB0_584
